# also nontemporal: P7/P10 residual loads and output stores, P8 row loads
# baseline (speedup 1.0000x reference)
;     __device__ __forceinline__ void operator()(const f32x4 (&acc)[2][2][4][2], const Unit& u, int wr, int wc, int fr, int fq) const {
;     ...
;             for (int n = 0; n < 2; ++n) gv[bj][n] = *(const f32x4*)(gp + col0 + bj * HALF + n * 16);
; #pragma unroll
;         for (int ai = 0; ai < 2; ++ai)
; #pragma unroll
;             for (int m = 0; m < 4; ++m) { const size_t off = (size_t)(u.pm * BM + ai * HALF + wr * 64 + m * 16 + fr) * 2048 + col0;
; #pragma unroll
;                 for (int bj = 0; bj < 2; ++bj)
; #pragma unroll
;                     for (int n = 0; n < 2; ++n) { const f32x4 bs = *(const f32x4*)(base + off + bj * HALF + n * 16);
;                         *(f32x4*)(out + off + bj * HALF + n * 16) = bs + gv[bj][n] * acc[ai][bj][m][n]; }
;                 if (m & 1) asm volatile("" ::: "memory"); }
.LBB0_944:
	v_lshl_add_u32 v160, s28, 8, v162
	s_ashr_i32 s21, s28, 5
	v_lshl_or_b32 v158, s48, 8, v164
	s_mul_hi_i32 s23, s21, 0xc000
	s_mul_i32 s21, s21, 0xc000
	v_ashrrev_i32_e32 v159, 31, v158
	s_add_u32 s30, s40, s21
	s_addc_u32 s31, s41, s23
	v_lshl_add_u64 v[130:131], v[158:159], 2, s[30:31]
	v_lshlrev_b32_e32 v172, 13, v160
	global_load_dwordx4 v[142:145], v[130:131], off
	global_load_dwordx4 v[138:141], v[130:131], off offset:64
	global_load_dwordx4 v[134:137], v[130:131], off offset:512
	v_lshl_add_u32 v172, v158, 2, v172
	global_load_dwordx4 v[130:133], v[130:131], off offset:576
	v_add_u32_e32 v173, 0x20000, v172
	v_add_u32_e32 v174, 0x40000, v172
	v_add_u32_e32 v175, 0x60000, v172
	v_add_u32_e32 v176, 0x100000, v172
	v_add_u32_e32 v177, 0x120000, v172
	v_add_u32_e32 v178, 0x140000, v172
	v_add_u32_e32 v179, 0x160000, v172
	global_load_dwordx4 v[188:191], v172, s[80:81] nt
	global_load_dwordx4 v[192:195], v172, s[80:81] offset:64 nt
	global_load_dwordx4 v[196:199], v172, s[80:81] offset:512 nt
	global_load_dwordx4 v[200:203], v172, s[80:81] offset:576 nt
	global_load_dwordx4 v[204:207], v173, s[80:81] nt
	global_load_dwordx4 v[208:211], v173, s[80:81] offset:64 nt
	global_load_dwordx4 v[212:215], v173, s[80:81] offset:512 nt
	global_load_dwordx4 v[216:219], v173, s[80:81] offset:576 nt
	global_load_dwordx4 v[220:223], v174, s[80:81] nt
	global_load_dwordx4 v[224:227], v174, s[80:81] offset:64 nt
	global_load_dwordx4 v[228:231], v174, s[80:81] offset:512 nt
	global_load_dwordx4 v[232:235], v174, s[80:81] offset:576 nt
	global_load_dwordx4 v[236:239], v175, s[80:81] nt
	global_load_dwordx4 v[240:243], v175, s[80:81] offset:64 nt
	global_load_dwordx4 v[244:247], v175, s[80:81] offset:512 nt
	global_load_dwordx4 v[180:183], v175, s[80:81] offset:576 nt
	s_andn2_b64 vcc, exec, s[0:1]
	s_mov_b64 s[0:1], -1
	s_waitcnt vmcnt(12)
	v_pk_fma_f32 v[126:127], v[126:127], v[142:143], v[188:189]
	v_pk_fma_f32 v[128:129], v[128:129], v[144:145], v[190:191]
	v_pk_fma_f32 v[122:123], v[122:123], v[138:139], v[192:193]
	v_pk_fma_f32 v[124:125], v[124:125], v[140:141], v[194:195]
	v_pk_fma_f32 v[118:119], v[118:119], v[134:135], v[196:197]
	v_pk_fma_f32 v[120:121], v[120:121], v[136:137], v[198:199]
	v_pk_fma_f32 v[106:107], v[106:107], v[130:131], v[200:201]
	v_pk_fma_f32 v[108:109], v[108:109], v[132:133], v[202:203]
	global_store_dwordx4 v172, v[126:129], s[12:13] nt
	global_store_dwordx4 v172, v[122:125], s[12:13] offset:64 nt
	global_store_dwordx4 v172, v[118:121], s[12:13] offset:512 nt
	global_store_dwordx4 v172, v[106:109], s[12:13] offset:576 nt
	global_load_dwordx4 v[188:191], v176, s[80:81] nt
	global_load_dwordx4 v[192:195], v176, s[80:81] offset:64 nt
	global_load_dwordx4 v[196:199], v176, s[80:81] offset:512 nt
	global_load_dwordx4 v[200:203], v176, s[80:81] offset:576 nt
	s_waitcnt vmcnt(16)
	v_pk_fma_f32 v[114:115], v[114:115], v[142:143], v[204:205]
	v_pk_fma_f32 v[116:117], v[116:117], v[144:145], v[206:207]
	v_pk_fma_f32 v[110:111], v[110:111], v[138:139], v[208:209]
	v_pk_fma_f32 v[112:113], v[112:113], v[140:141], v[210:211]
	v_pk_fma_f32 v[102:103], v[102:103], v[134:135], v[212:213]
	v_pk_fma_f32 v[104:105], v[104:105], v[136:137], v[214:215]
	v_pk_fma_f32 v[90:91], v[90:91], v[130:131], v[216:217]
	v_pk_fma_f32 v[92:93], v[92:93], v[132:133], v[218:219]
	global_store_dwordx4 v173, v[114:117], s[12:13] nt
	global_store_dwordx4 v173, v[110:113], s[12:13] offset:64 nt
	global_store_dwordx4 v173, v[102:105], s[12:13] offset:512 nt
	global_store_dwordx4 v173, v[90:93], s[12:13] offset:576 nt
	global_load_dwordx4 v[204:207], v177, s[80:81] nt
	global_load_dwordx4 v[208:211], v177, s[80:81] offset:64 nt
	global_load_dwordx4 v[212:215], v177, s[80:81] offset:512 nt
	global_load_dwordx4 v[216:219], v177, s[80:81] offset:576 nt
	s_waitcnt vmcnt(20)
	v_pk_fma_f32 v[98:99], v[98:99], v[142:143], v[220:221]
	v_pk_fma_f32 v[100:101], v[100:101], v[144:145], v[222:223]
	v_pk_fma_f32 v[94:95], v[94:95], v[138:139], v[224:225]
	v_pk_fma_f32 v[96:97], v[96:97], v[140:141], v[226:227]
	v_pk_fma_f32 v[86:87], v[86:87], v[134:135], v[228:229]
	v_pk_fma_f32 v[88:89], v[88:89], v[136:137], v[230:231]
	v_pk_fma_f32 v[74:75], v[74:75], v[130:131], v[232:233]
	v_pk_fma_f32 v[76:77], v[76:77], v[132:133], v[234:235]
	global_store_dwordx4 v174, v[98:101], s[12:13] nt
	global_store_dwordx4 v174, v[94:97], s[12:13] offset:64 nt
	global_store_dwordx4 v174, v[86:89], s[12:13] offset:512 nt
	global_store_dwordx4 v174, v[74:77], s[12:13] offset:576 nt
	global_load_dwordx4 v[220:223], v178, s[80:81] nt
	global_load_dwordx4 v[224:227], v178, s[80:81] offset:64 nt
	global_load_dwordx4 v[228:231], v178, s[80:81] offset:512 nt
	global_load_dwordx4 v[232:235], v178, s[80:81] offset:576 nt
	s_waitcnt vmcnt(24)
;     __device__ __forceinline__ void operator()(const f32x4 (&acc)[2][2][4][2], const Unit& u, int wr, int wc, int fr, int fq) const {
;     ...
;             for (int m = 0; m < 4; ++m) { const size_t off = (size_t)(u.pm * BM + ai * HALF + wr * 64 + m * 16 + fr) * 2048 + col0;
; #pragma unroll
;                 for (int bj = 0; bj < 2; ++bj)
; #pragma unroll
;                     for (int n = 0; n < 2; ++n) { const f32x4 bs = *(const f32x4*)(base + off + bj * HALF + n * 16);
;                         *(f32x4*)(out + off + bj * HALF + n * 16) = bs + gv[bj][n] * acc[ai][bj][m][n]; }
;                 if (m & 1) asm volatile("" ::: "memory"); }
	v_pk_fma_f32 v[82:83], v[82:83], v[142:143], v[236:237]
	v_pk_fma_f32 v[84:85], v[84:85], v[144:145], v[238:239]
	v_pk_fma_f32 v[78:79], v[78:79], v[138:139], v[240:241]
	v_pk_fma_f32 v[80:81], v[80:81], v[140:141], v[242:243]
	v_pk_fma_f32 v[70:71], v[70:71], v[134:135], v[244:245]
	v_pk_fma_f32 v[72:73], v[72:73], v[136:137], v[246:247]
	v_pk_fma_f32 v[66:67], v[66:67], v[130:131], v[180:181]
	v_pk_fma_f32 v[68:69], v[68:69], v[132:133], v[182:183]
	global_store_dwordx4 v175, v[82:85], s[12:13] nt
	global_store_dwordx4 v175, v[78:81], s[12:13] offset:64 nt
	global_store_dwordx4 v175, v[70:73], s[12:13] offset:512 nt
	global_store_dwordx4 v175, v[66:69], s[12:13] offset:576 nt
	global_load_dwordx4 v[236:239], v179, s[80:81] nt
	global_load_dwordx4 v[240:243], v179, s[80:81] offset:64 nt
	global_load_dwordx4 v[244:247], v179, s[80:81] offset:512 nt
	global_load_dwordx4 v[180:183], v179, s[80:81] offset:576 nt
	s_waitcnt vmcnt(24)
	v_pk_fma_f32 v[62:63], v[62:63], v[142:143], v[188:189]
	v_pk_fma_f32 v[64:65], v[64:65], v[144:145], v[190:191]
	v_pk_fma_f32 v[58:59], v[58:59], v[138:139], v[192:193]
	v_pk_fma_f32 v[60:61], v[60:61], v[140:141], v[194:195]
	v_pk_fma_f32 v[54:55], v[54:55], v[134:135], v[196:197]
	v_pk_fma_f32 v[56:57], v[56:57], v[136:137], v[198:199]
	v_pk_fma_f32 v[42:43], v[42:43], v[130:131], v[200:201]
	v_pk_fma_f32 v[44:45], v[44:45], v[132:133], v[202:203]
	global_store_dwordx4 v176, v[62:65], s[12:13] nt
	global_store_dwordx4 v176, v[58:61], s[12:13] offset:64 nt
	global_store_dwordx4 v176, v[54:57], s[12:13] offset:512 nt
	global_store_dwordx4 v176, v[42:45], s[12:13] offset:576 nt
	s_waitcnt vmcnt(20)
	v_pk_fma_f32 v[50:51], v[50:51], v[142:143], v[204:205]
	v_pk_fma_f32 v[52:53], v[52:53], v[144:145], v[206:207]
	v_pk_fma_f32 v[46:47], v[46:47], v[138:139], v[208:209]
	v_pk_fma_f32 v[48:49], v[48:49], v[140:141], v[210:211]
	v_pk_fma_f32 v[38:39], v[38:39], v[134:135], v[212:213]
	v_pk_fma_f32 v[40:41], v[40:41], v[136:137], v[214:215]
	v_pk_fma_f32 v[26:27], v[26:27], v[130:131], v[216:217]
	v_pk_fma_f32 v[28:29], v[28:29], v[132:133], v[218:219]
	global_store_dwordx4 v177, v[50:53], s[12:13] nt
	global_store_dwordx4 v177, v[46:49], s[12:13] offset:64 nt
	global_store_dwordx4 v177, v[38:41], s[12:13] offset:512 nt
	global_store_dwordx4 v177, v[26:29], s[12:13] offset:576 nt
	s_waitcnt vmcnt(16)
	v_pk_fma_f32 v[34:35], v[34:35], v[142:143], v[220:221]
	v_pk_fma_f32 v[36:37], v[36:37], v[144:145], v[222:223]
	v_pk_fma_f32 v[30:31], v[30:31], v[138:139], v[224:225]
	v_pk_fma_f32 v[32:33], v[32:33], v[140:141], v[226:227]
	v_pk_fma_f32 v[22:23], v[22:23], v[134:135], v[228:229]
	v_pk_fma_f32 v[24:25], v[24:25], v[136:137], v[230:231]
	v_pk_fma_f32 v[10:11], v[10:11], v[130:131], v[232:233]
	v_pk_fma_f32 v[12:13], v[12:13], v[132:133], v[234:235]
	global_store_dwordx4 v178, v[34:37], s[12:13] nt
	global_store_dwordx4 v178, v[30:33], s[12:13] offset:64 nt
	global_store_dwordx4 v178, v[22:25], s[12:13] offset:512 nt
	global_store_dwordx4 v178, v[10:13], s[12:13] offset:576 nt
	s_waitcnt vmcnt(12)
	v_pk_fma_f32 v[18:19], v[18:19], v[142:143], v[236:237]
	v_pk_fma_f32 v[20:21], v[20:21], v[144:145], v[238:239]
	v_pk_fma_f32 v[14:15], v[14:15], v[138:139], v[240:241]
	v_pk_fma_f32 v[16:17], v[16:17], v[140:141], v[242:243]
	v_pk_fma_f32 v[6:7], v[6:7], v[134:135], v[244:245]
	v_pk_fma_f32 v[8:9], v[8:9], v[136:137], v[246:247]
	v_pk_fma_f32 v[2:3], v[2:3], v[130:131], v[180:181]
	v_pk_fma_f32 v[4:5], v[4:5], v[132:133], v[182:183]
	global_store_dwordx4 v179, v[18:21], s[12:13] nt
	global_store_dwordx4 v179, v[14:17], s[12:13] offset:64 nt
	global_store_dwordx4 v179, v[6:9], s[12:13] offset:512 nt
	global_store_dwordx4 v179, v[2:5], s[12:13] offset:576 nt
	s_cbranch_vccnz .LBB0_933
	s_andn2_b64 vcc, exec, s[6:7]
	s_cbranch_vccnz .LBB0_932
	s_barrier
	s_branch .LBB0_932

; template <bool NT_LD, bool NT_ST> DI void norm_row2(const float* xrow0, const float* xrow1, const float* g, const float* sc, const float* sh, bf16* obf0, bf16* obf1, float* of0, float* of1, int lane) {
;     ...
; #pragma unroll
;     for (int j = 0; j < 8; ++j) { if (NT_LD) { v0[j] = __builtin_nontemporal_load(xr0 + 64 * j); v1[j] = __builtin_nontemporal_load(xr1 + 64 * j); } else { v0[j] = xr0[64 * j]; v1[j] = xr1[64 * j]; } }
; #pragma unroll
;     for (int j = 0; j < 8; ++j) { s0 += (v0[j].x * v0[j].x + v0[j].y * v0[j].y) + (v0[j].z * v0[j].z + v0[j].w * v0[j].w); s1 += (v1[j].x * v1[j].x + v1[j].y * v1[j].y) + (v1[j].z * v1[j].z + v1[j].w * v1[j].w); }
; #pragma unroll
;     for (int o = 1; o < 64; o <<= 1) { s0 += __shfl_xor(s0, o); s1 += __shfl_xor(s1, o); }
;     const float r0 = 1.0f / sqrtf(s0 * (1.0f / DM) + EPS), r1 = 1.0f / sqrtf(s1 * (1.0f / DM) + EPS);
; __global__ void __launch_bounds__(512, 2) fwd_mega(Args args) {
;     ...
;         for (int m = 2 * gw; m < M; m += 2 * NGW) { const int b = m >> 13; norm_row2<false, false>(out + (size_t)m * DM, out + (size_t)(m + 1) * DM, norm2_g, modall + b * NMOD + 4 * DM, modall + b * NMOD + 3 * DM, H2 + (size_t)m * DM, H2 + (size_t)(m + 1) * DM, nullptr, nullptr, lane); }
.LBB0_1019:
	global_load_dwordx4 v[10:13], v[76:77], off nt
	global_load_dwordx4 v[14:17], v[76:77], off offset:1024 nt
	v_add_co_u32_e32 v18, vcc, 0x2000, v76
	s_waitcnt lgkmcnt(6)
	global_load_dwordx4 v[6:9], v[76:77], off offset:2048 nt
	global_load_dwordx4 v[2:5], v[76:77], off offset:3072 nt
	global_load_dwordx4 v[58:61], v[64:65], off
	v_addc_co_u32_e32 v19, vcc, 0, v77, vcc
	v_add_co_u32_e32 v22, vcc, 0x1000, v76
	global_load_dwordx4 v[98:101], v[18:19], off nt
	global_load_dwordx4 v[102:105], v[18:19], off offset:1024 nt
	global_load_dwordx4 v[54:57], v[18:19], off offset:2048 nt
	global_load_dwordx4 v[50:53], v[18:19], off offset:3072 nt
	v_addc_co_u32_e32 v23, vcc, 0, v77, vcc
	v_add_co_u32_e32 v80, vcc, s3, v76
	global_load_dwordx4 v[42:45], v[22:23], off nt
	global_load_dwordx4 v[34:37], v[22:23], off offset:1024 nt
	global_load_dwordx4 v[18:21], v[22:23], off offset:3072 nt
	global_load_dwordx4 v[26:29], v[22:23], off offset:2048 nt
	v_addc_co_u32_e32 v81, vcc, 0, v77, vcc
	global_load_dwordx4 v[46:49], v[80:81], off nt
	global_load_dwordx4 v[38:41], v[80:81], off offset:1024 nt
	global_load_dwordx4 v[30:33], v[80:81], off offset:2048 nt
	global_load_dwordx4 v[22:25], v[80:81], off offset:3072 nt
	v_add_co_u32_e64 v78, s[0:1], s9, v74
	s_ashr_i32 s4, s8, 13
	s_nop 0
	v_addc_co_u32_e64 v79, s[0:1], 0, v75, s[0:1]
	s_mul_i32 s0, s4, 0x3000
	s_ashr_i32 s1, s0, 31
	s_lshl_b64 s[0:1], s[0:1], 2
	s_add_u32 s0, s14, s0
	s_addc_u32 s1, s15, s1
	v_lshl_add_u64 v[82:83], v[62:63], 4, s[0:1]
	v_add_co_u32_e32 v80, vcc, s26, v82
	v_lshl_add_u64 v[86:87], v[82:83], 0, s[22:23]
	s_nop 0
	v_addc_co_u32_e32 v81, vcc, 0, v83, vcc
	v_lshl_add_u64 v[88:89], v[82:83], 0, s[24:25]
	v_add_co_u32_e32 v82, vcc, s27, v82
	s_add_i32 s8, s8, s16
	s_nop 0
	v_addc_co_u32_e32 v83, vcc, 0, v83, vcc
	global_load_dwordx4 v[106:109], v[80:81], off offset:-4096
	global_load_dwordx4 v[110:113], v[82:83], off offset:-4096
	v_lshl_add_u64 v[76:77], v[76:77], 0, s[20:21]
	s_cmp_lt_i32 s8, 0x8000
	s_waitcnt vmcnt(18)
	v_mov_b32_e32 v116, v11
	s_waitcnt vmcnt(17)
	v_mov_b32_e32 v117, v15
	v_mov_b32_e32 v120, v13
	v_mov_b32_e32 v121, v17
	v_mov_b32_e32 v114, v10
	v_mov_b32_e32 v115, v14
	v_mov_b32_e32 v118, v12
	v_mov_b32_e32 v119, v16
	s_waitcnt vmcnt(16)
	v_pk_mul_f32 v[122:123], v[8:9], v[8:9]
	v_pk_mul_f32 v[124:125], v[6:7], v[6:7]
	v_pk_mul_f32 v[116:117], v[116:117], v[116:117]
	v_pk_mul_f32 v[120:121], v[120:121], v[120:121]
	s_waitcnt vmcnt(15)
	v_mul_f32_e32 v84, v3, v3
	v_mul_f32_e32 v126, v5, v5
	v_pk_mov_b32 v[128:129], v[124:125], v[122:123] op_sel:[1,0]
	v_mov_b32_e32 v125, v123
	v_pk_fma_f32 v[114:115], v[114:115], v[114:115], v[116:117]
	v_pk_fma_f32 v[116:117], v[118:119], v[118:119], v[120:121]
	s_waitcnt vmcnt(13)
	v_mov_b32_e32 v120, v99
	s_waitcnt vmcnt(12)
	v_mov_b32_e32 v121, v103
	v_mov_b32_e32 v132, v101
	v_mov_b32_e32 v133, v105
	v_pk_fma_f32 v[122:123], v[2:3], v[2:3], v[84:85] op_sel_hi:[1,1,0]
	v_pk_fma_f32 v[126:127], v[4:5], v[4:5], v[126:127] op_sel_hi:[1,1,0]
	v_mov_b32_e32 v118, v98
	v_mov_b32_e32 v119, v102
	v_mov_b32_e32 v130, v100
	v_mov_b32_e32 v131, v104
	v_pk_add_f32 v[124:125], v[128:129], v[124:125]
	s_waitcnt vmcnt(11)
	v_pk_mul_f32 v[128:129], v[56:57], v[56:57]
	v_pk_mul_f32 v[134:135], v[54:55], v[54:55]
	v_pk_add_f32 v[114:115], v[114:115], v[116:117]
	v_pk_mul_f32 v[116:117], v[120:121], v[120:121]
	v_pk_mul_f32 v[120:121], v[132:133], v[132:133]
	v_pk_mov_b32 v[132:133], v[134:135], v[128:129] op_sel:[1,0]
	v_mov_b32_e32 v135, v129
	s_waitcnt vmcnt(9)
	v_mul_f32_e32 v97, v42, v42
	v_mul_f32_e32 v123, v43, v43
	v_mul_f32_e32 v127, v44, v44
	v_mul_f32_e32 v143, v45, v45
	v_pk_add_f32 v[124:125], v[124:125], v[124:125] op_sel:[0,1] op_sel_hi:[1,0]
	v_pk_fma_f32 v[116:117], v[118:119], v[118:119], v[116:117]
	v_pk_fma_f32 v[118:119], v[130:131], v[130:131], v[120:121]
	v_pk_add_f32 v[114:115], v[114:115], v[114:115] op_sel:[0,1] op_sel_hi:[1,0]
	v_mul_f32_e32 v84, v51, v51
	v_mul_f32_e32 v136, v53, v53
	s_waitcnt vmcnt(8)
	v_pk_mul_f32 v[138:139], v[36:37], v[36:37]
	v_pk_mul_f32 v[140:141], v[34:35], v[34:35]
	v_pk_add_f32 v[120:121], v[132:133], v[134:135]
	v_mov_b32_e32 v125, v123
	v_mov_b32_e32 v123, v127
	v_mov_b32_e32 v127, v143
	v_pk_add_f32 v[116:117], v[116:117], v[118:119]
	v_mov_b32_e32 v115, v97
	v_pk_fma_f32 v[128:129], v[50:51], v[50:51], v[84:85] op_sel_hi:[1,1,0]
	v_pk_fma_f32 v[136:137], v[52:53], v[52:53], v[136:137] op_sel_hi:[1,1,0]
	s_waitcnt vmcnt(5)
	v_mul_f32_e32 v149, v46, v46
	v_mul_f32_e32 v150, v47, v47
	v_pk_mov_b32 v[130:131], v[140:141], v[138:139] op_sel:[1,0]
	v_mov_b32_e32 v141, v139
	v_pk_add_f32 v[118:119], v[122:123], v[126:127]
	v_pk_add_f32 v[120:121], v[120:121], v[120:121] op_sel:[0,1] op_sel_hi:[1,0]
	v_pk_add_f32 v[114:115], v[114:115], v[124:125]
	v_pk_add_f32 v[116:117], v[116:117], v[116:117] op_sel:[0,1] op_sel_hi:[1,0]
	v_mul_f32_e32 v84, v27, v27
	v_mul_f32_e32 v142, v29, v29
	v_mul_f32_e32 v129, v48, v48
	v_mul_f32_e32 v137, v49, v49
	s_waitcnt vmcnt(4)
	v_pk_mul_f32 v[132:133], v[40:41], v[40:41]
	v_pk_mul_f32 v[134:135], v[38:39], v[38:39]
	v_pk_add_f32 v[122:123], v[130:131], v[140:141]
	v_mov_b32_e32 v121, v150
	v_pk_add_f32 v[114:115], v[114:115], v[118:119]
	v_mov_b32_e32 v117, v149
	v_mul_f32_e32 v145, v18, v18
	v_mul_f32_e32 v146, v19, v19
	v_mul_f32_e32 v147, v20, v20
	v_mul_f32_e32 v148, v21, v21
	v_pk_fma_f32 v[138:139], v[26:27], v[26:27], v[84:85] op_sel_hi:[1,1,0]
	v_pk_fma_f32 v[142:143], v[28:29], v[28:29], v[142:143] op_sel_hi:[1,1,0]
	v_pk_mov_b32 v[126:127], v[134:135], v[132:133] op_sel:[1,0]
	v_mov_b32_e32 v135, v133
	v_pk_add_f32 v[124:125], v[128:129], v[136:137]
	v_pk_add_f32 v[122:123], v[122:123], v[122:123] op_sel:[0,1] op_sel_hi:[1,0]
	v_pk_add_f32 v[116:117], v[116:117], v[120:121]
	v_pk_add_f32 v[114:115], v[114:115], v[114:115] op_sel:[0,1] op_sel_hi:[1,0]
	s_waitcnt vmcnt(3)
; template <bool NT_LD, bool NT_ST> DI void norm_row2(const float* xrow0, const float* xrow1, const float* g, const float* sc, const float* sh, bf16* obf0, bf16* obf1, float* of0, float* of1, int lane) {
;     ...
;     for (int o = 1; o < 64; o <<= 1) { s0 += __shfl_xor(s0, o); s1 += __shfl_xor(s1, o); }
;     const float r0 = 1.0f / sqrtf(s0 * (1.0f / DM) + EPS), r1 = 1.0f / sqrtf(s1 * (1.0f / DM) + EPS);
; #pragma unroll
;     for (int j = 0; j < 8; ++j) {
;         const int c4 = lane + 64 * j;
;         const f32x4 gg = ((const f32x4*)g)[c4];
;         f32x4 y0 = v0[j] * r0 * gg, y1 = v1[j] * r1 * gg;
;         if (sc) { const f32x4 a = ((const f32x4*)sc)[c4] + 1.0f, bsh = ((const f32x4*)sh)[c4]; y0 = y0 * a + bsh; y1 = y1 * a + bsh; }
	v_mul_f32_e32 v84, v31, v31
	v_mul_f32_e32 v144, v33, v33
	v_mov_b32_e32 v139, v147
	v_mov_b32_e32 v143, v148
	v_pk_add_f32 v[126:127], v[126:127], v[134:135]
	v_mov_b32_e32 v123, v146
	v_pk_add_f32 v[116:117], v[116:117], v[124:125]
	v_mov_b32_e32 v115, v145
	s_waitcnt vmcnt(2)
	v_mul_f32_e32 v151, v22, v22
	v_mul_f32_e32 v152, v23, v23
	v_mul_f32_e32 v153, v24, v24
	v_mul_f32_e32 v154, v25, v25
	v_pk_fma_f32 v[130:131], v[30:31], v[30:31], v[84:85] op_sel_hi:[1,1,0]
	v_pk_fma_f32 v[132:133], v[32:33], v[32:33], v[144:145] op_sel_hi:[1,1,0]
	v_pk_add_f32 v[128:129], v[138:139], v[142:143]
	v_pk_add_f32 v[118:119], v[126:127], v[126:127] op_sel:[0,1] op_sel_hi:[1,0]
	v_pk_add_f32 v[114:115], v[114:115], v[122:123]
	v_pk_add_f32 v[116:117], v[116:117], v[116:117] op_sel:[0,1] op_sel_hi:[1,0]
	v_mov_b32_e32 v131, v153
	v_mov_b32_e32 v133, v154
	v_mov_b32_e32 v119, v152
	v_pk_add_f32 v[114:115], v[114:115], v[128:129]
	v_mov_b32_e32 v117, v151
	v_pk_add_f32 v[126:127], v[130:131], v[132:133]
	v_add_f32_e32 v84, v114, v115
	v_pk_add_f32 v[114:115], v[116:117], v[118:119]
	ds_bpermute_b32 v97, v85, v84
	v_pk_add_f32 v[114:115], v[114:115], v[126:127]
	s_waitcnt vmcnt(1)
	v_pk_add_f32 v[108:109], v[108:109], 1.0 op_sel_hi:[1,0]
	v_add_f32_e32 v114, v114, v115
	ds_bpermute_b32 v115, v85, v114
	s_waitcnt lgkmcnt(1)
	v_add_f32_e32 v84, v84, v97
	ds_bpermute_b32 v97, v90, v84
	v_pk_add_f32 v[106:107], v[106:107], 1.0 op_sel_hi:[1,0]
	s_waitcnt lgkmcnt(1)
	v_add_f32_e32 v114, v114, v115
	ds_bpermute_b32 v115, v90, v114
	s_waitcnt lgkmcnt(1)
	v_add_f32_e32 v84, v84, v97
	ds_bpermute_b32 v97, v91, v84
	s_waitcnt lgkmcnt(1)
	v_add_f32_e32 v114, v114, v115
	ds_bpermute_b32 v115, v91, v114
	s_waitcnt lgkmcnt(1)
	v_add_f32_e32 v84, v84, v97
	ds_bpermute_b32 v97, v92, v84
	s_waitcnt lgkmcnt(1)
	v_add_f32_e32 v114, v114, v115
	ds_bpermute_b32 v115, v92, v114
	s_waitcnt lgkmcnt(1)
	v_add_f32_e32 v84, v84, v97
	ds_bpermute_b32 v97, v93, v84
	s_waitcnt lgkmcnt(1)
	v_add_f32_e32 v114, v114, v115
	ds_bpermute_b32 v115, v93, v114
	s_waitcnt lgkmcnt(1)
	v_add_f32_e32 v84, v84, v97
	ds_bpermute_b32 v97, v94, v84
	s_waitcnt lgkmcnt(1)
	v_add_f32_e32 v114, v114, v115
	ds_bpermute_b32 v115, v94, v114
	s_waitcnt lgkmcnt(1)
	v_add_f32_e32 v84, v84, v97
	v_fmamk_f32 v84, v84, 0x3a000000, v95
	v_cmp_gt_f32_e32 vcc, s17, v84
	s_waitcnt lgkmcnt(0)
	v_add_f32_e32 v97, v114, v115
	v_mul_f32_e32 v114, 0x4f800000, v84
	v_cndmask_b32_e32 v84, v84, v114, vcc
	v_fmamk_f32 v97, v97, 0x3a000000, v95
	v_sqrt_f32_e32 v114, v84
	v_mul_f32_e32 v115, 0x4f800000, v97
	v_cmp_gt_f32_e64 s[0:1], s17, v97
	v_add_u32_e32 v116, -1, v114
	s_nop 0
	v_cndmask_b32_e64 v97, v97, v115, s[0:1]
	v_sqrt_f32_e32 v115, v97
	v_add_u32_e32 v117, 1, v114
	v_fma_f32 v118, -v116, v114, v84
	v_fma_f32 v119, -v117, v114, v84
	v_cmp_ge_f32_e64 s[4:5], 0, v118
	v_add_u32_e32 v118, 1, v115
	s_nop 0
	v_cndmask_b32_e64 v114, v114, v116, s[4:5]
	v_add_u32_e32 v116, -1, v115
	v_cmp_lt_f32_e64 s[4:5], 0, v119
	v_fma_f32 v119, -v118, v115, v97
	s_nop 0
	v_cndmask_b32_e64 v114, v114, v117, s[4:5]
	v_fma_f32 v117, -v116, v115, v97
	v_cmp_ge_f32_e64 s[4:5], 0, v117
	v_mul_f32_e32 v120, 0x37800000, v114
	v_cndmask_b32_e32 v114, v114, v120, vcc
	v_cndmask_b32_e64 v115, v115, v116, s[4:5]
	v_cmp_lt_f32_e64 s[4:5], 0, v119
	v_cmp_class_f32_e32 vcc, v84, v96
	s_nop 0
	v_cndmask_b32_e64 v115, v115, v118, s[4:5]
	v_cndmask_b32_e32 v84, v114, v84, vcc
	v_mul_f32_e32 v114, 0x37800000, v115
	v_div_scale_f32 v116, s[4:5], v84, v84, 1.0
	v_cndmask_b32_e64 v114, v115, v114, s[0:1]
	v_cmp_class_f32_e64 s[0:1], v97, v96
	v_rcp_f32_e32 v115, v116
	v_div_scale_f32 v117, vcc, 1.0, v84, 1.0
	v_cndmask_b32_e64 v97, v114, v97, s[0:1]
	v_div_scale_f32 v114, s[0:1], v97, v97, 1.0
	v_rcp_f32_e32 v119, v114
	v_fma_f32 v120, -v116, v115, 1.0
	v_fmac_f32_e32 v115, v120, v115
	v_mul_f32_e32 v120, v117, v115
	v_fma_f32 v121, -v114, v119, 1.0
	v_div_scale_f32 v118, s[0:1], 1.0, v97, 1.0
	v_fma_f32 v122, -v116, v120, v117
	v_fmac_f32_e32 v119, v121, v119
	v_fmac_f32_e32 v120, v122, v115
	v_mul_f32_e32 v121, v118, v119
	v_fma_f32 v116, -v116, v120, v117
	v_fma_f32 v117, -v114, v121, v118
	v_fmac_f32_e32 v121, v117, v119
	v_div_fmas_f32 v115, v116, v115, v120
	v_fma_f32 v114, -v114, v121, v118
	s_mov_b64 vcc, s[0:1]
	v_div_fixup_f32 v84, v115, v84, 1.0
	v_div_fmas_f32 v118, v114, v119, v121
	v_pk_mul_f32 v[12:13], v[12:13], v[84:85] op_sel_hi:[1,0]
	v_pk_mul_f32 v[114:115], v[10:11], v[84:85] op_sel_hi:[1,0]
	v_div_fixup_f32 v10, v118, v97, 1.0
	v_pk_mul_f32 v[116:117], v[14:15], v[84:85] op_sel_hi:[1,0]
	v_pk_mul_f32 v[14:15], v[58:59], v[114:115]
	v_pk_mul_f32 v[12:13], v[60:61], v[12:13]
	v_pk_mul_f32 v[100:101], v[100:101], v[10:11] op_sel_hi:[1,0]
	v_pk_mul_f32 v[98:99], v[98:99], v[10:11] op_sel_hi:[1,0]
	s_waitcnt vmcnt(0)
; DI unsigned pk2(float lo, float hi) { f32x2_t v = {lo, hi}; bf16x2_t b = __builtin_convertvector(v, bf16x2_t); return __builtin_bit_cast(unsigned, b); }
; template <bool NT_LD, bool NT_ST> DI void norm_row2(const float* xrow0, const float* xrow1, const float* g, const float* sc, const float* sh, bf16* obf0, bf16* obf1, float* of0, float* of1, int lane) {
;     ...
;     for (int j = 0; j < 8; ++j) {
;         const int c4 = lane + 64 * j;
;         const f32x4 gg = ((const f32x4*)g)[c4];
;         f32x4 y0 = v0[j] * r0 * gg, y1 = v1[j] * r1 * gg;
;         if (sc) { const f32x4 a = ((const f32x4*)sc)[c4] + 1.0f, bsh = ((const f32x4*)sh)[c4]; y0 = y0 * a + bsh; y1 = y1 * a + bsh; }
;         if (obf0) { u32x2 o0; o0.x = pk2(y0.x, y0.y); o0.y = pk2(y0.z, y0.w); ((u32x2*)obf0)[c4] = o0; u32x2 o1; o1.x = pk2(y1.x, y1.y); o1.y = pk2(y1.z, y1.w); ((u32x2*)obf1)[c4] = o1; }
;         else if (NT_ST) { __builtin_nontemporal_store(y0, (f32x4*)of0 + c4); __builtin_nontemporal_store(y1, (f32x4*)of1 + c4); }
;         else { ((f32x4*)of0)[c4] = y0; ((f32x4*)of1)[c4] = y1; }
	v_pk_fma_f32 v[12:13], v[108:109], v[12:13], v[112:113]
	v_pk_fma_f32 v[14:15], v[106:107], v[14:15], v[110:111]
	v_pk_mul_f32 v[58:59], v[58:59], v[98:99]
	v_pk_mul_f32 v[60:61], v[60:61], v[100:101]
	v_cvt_pk_bf16_f32 v14, v14, v15
	v_cvt_pk_bf16_f32 v15, v12, v13
	v_pk_fma_f32 v[12:13], v[108:109], v[60:61], v[112:113]
	v_pk_fma_f32 v[58:59], v[106:107], v[58:59], v[110:111]
	global_store_dwordx2 v[74:75], v[14:15], off
	v_cvt_pk_bf16_f32 v14, v58, v59
	v_cvt_pk_bf16_f32 v15, v12, v13
	global_store_dwordx2 v[78:79], v[14:15], off
	global_load_dwordx4 v[12:15], v[64:65], off offset:1024
	s_nop 0
	global_load_dwordx4 v[58:61], v[86:87], off offset:1024
	global_load_dwordx4 v[98:101], v[88:89], off offset:1024
	v_pk_mul_f32 v[16:17], v[16:17], v[84:85] op_sel_hi:[1,0]
	v_pk_mul_f32 v[104:105], v[104:105], v[10:11] op_sel_hi:[1,0]
	v_pk_mul_f32 v[102:103], v[102:103], v[10:11] op_sel_hi:[1,0]
	v_pk_mul_f32 v[8:9], v[8:9], v[84:85] op_sel_hi:[1,0]
	v_pk_mul_f32 v[6:7], v[6:7], v[84:85] op_sel_hi:[1,0]
	v_pk_mul_f32 v[54:55], v[54:55], v[10:11] op_sel_hi:[1,0]
	v_pk_mul_f32 v[4:5], v[4:5], v[84:85] op_sel_hi:[1,0]
	v_pk_mul_f32 v[2:3], v[2:3], v[84:85] op_sel_hi:[1,0]
	v_pk_mul_f32 v[50:51], v[50:51], v[10:11] op_sel_hi:[1,0]
	v_pk_mul_f32 v[42:43], v[42:43], v[84:85] op_sel_hi:[1,0]
	v_pk_mul_f32 v[46:47], v[46:47], v[10:11] op_sel_hi:[1,0]
	v_pk_mul_f32 v[34:35], v[34:35], v[84:85] op_sel_hi:[1,0]
	v_pk_mul_f32 v[38:39], v[38:39], v[10:11] op_sel_hi:[1,0]
	v_pk_mul_f32 v[26:27], v[26:27], v[84:85] op_sel_hi:[1,0]
	v_pk_mul_f32 v[30:31], v[30:31], v[10:11] op_sel_hi:[1,0]
	v_pk_mul_f32 v[18:19], v[18:19], v[84:85] op_sel_hi:[1,0]
	s_waitcnt vmcnt(2)
	v_pk_mul_f32 v[106:107], v[12:13], v[116:117]
	v_pk_mul_f32 v[16:17], v[14:15], v[16:17]
	s_waitcnt vmcnt(1)
	v_pk_add_f32 v[60:61], v[60:61], 1.0 op_sel_hi:[1,0]
	v_pk_add_f32 v[58:59], v[58:59], 1.0 op_sel_hi:[1,0]
	v_pk_mul_f32 v[12:13], v[12:13], v[102:103]
	v_pk_mul_f32 v[14:15], v[14:15], v[104:105]
	s_waitcnt vmcnt(0)
	v_pk_fma_f32 v[16:17], v[60:61], v[16:17], v[100:101]
	v_pk_fma_f32 v[102:103], v[58:59], v[106:107], v[98:99]
	v_pk_fma_f32 v[14:15], v[60:61], v[14:15], v[100:101]
	v_pk_fma_f32 v[12:13], v[58:59], v[12:13], v[98:99]
	v_cvt_pk_bf16_f32 v58, v102, v103
	v_cvt_pk_bf16_f32 v59, v16, v17
	v_cvt_pk_bf16_f32 v12, v12, v13
	v_cvt_pk_bf16_f32 v13, v14, v15
	global_store_dwordx2 v[74:75], v[58:59], off offset:512
	global_store_dwordx2 v[78:79], v[12:13], off offset:512
	global_load_dwordx4 v[12:15], v[64:65], off offset:2048
	s_nop 0
	global_load_dwordx4 v[58:61], v[86:87], off offset:2048
	global_load_dwordx4 v[98:101], v[88:89], off offset:2048
	v_pk_mul_f32 v[16:17], v[56:57], v[10:11] op_sel_hi:[1,0]
	s_waitcnt vmcnt(2)
	v_pk_mul_f32 v[6:7], v[6:7], v[12:13]
	v_pk_mul_f32 v[8:9], v[8:9], v[14:15]
	v_pk_mul_f32 v[12:13], v[54:55], v[12:13]
	v_pk_mul_f32 v[14:15], v[16:17], v[14:15]
	s_waitcnt vmcnt(1)
	v_pk_add_f32 v[16:17], v[60:61], 1.0 op_sel_hi:[1,0]
	v_pk_add_f32 v[54:55], v[58:59], 1.0 op_sel_hi:[1,0]
	s_waitcnt vmcnt(0)
	v_pk_fma_f32 v[8:9], v[8:9], v[16:17], v[100:101]
	v_pk_fma_f32 v[6:7], v[6:7], v[54:55], v[98:99]
	v_pk_fma_f32 v[14:15], v[14:15], v[16:17], v[100:101]
	v_pk_fma_f32 v[12:13], v[12:13], v[54:55], v[98:99]
	v_cvt_pk_bf16_f32 v6, v6, v7
	v_cvt_pk_bf16_f32 v7, v8, v9
	v_cvt_pk_bf16_f32 v8, v12, v13
	v_cvt_pk_bf16_f32 v9, v14, v15
	global_store_dwordx2 v[74:75], v[6:7], off offset:1024
	global_store_dwordx2 v[78:79], v[8:9], off offset:1024
	global_load_dwordx4 v[6:9], v[64:65], off offset:3072
	s_nop 0
	global_load_dwordx4 v[12:15], v[86:87], off offset:3072
	global_load_dwordx4 v[54:57], v[88:89], off offset:3072
	v_pk_mul_f32 v[16:17], v[52:53], v[10:11] op_sel_hi:[1,0]
	s_waitcnt vmcnt(2)
	v_pk_mul_f32 v[2:3], v[2:3], v[6:7]
	v_pk_mul_f32 v[4:5], v[4:5], v[8:9]
	s_waitcnt vmcnt(1)
	v_pk_add_f32 v[14:15], v[14:15], 1.0 op_sel_hi:[1,0]
	v_pk_add_f32 v[12:13], v[12:13], 1.0 op_sel_hi:[1,0]
	v_pk_mul_f32 v[6:7], v[50:51], v[6:7]
	v_pk_mul_f32 v[8:9], v[16:17], v[8:9]
	s_waitcnt vmcnt(0)
; DI unsigned pk2(float lo, float hi) { f32x2_t v = {lo, hi}; bf16x2_t b = __builtin_convertvector(v, bf16x2_t); return __builtin_bit_cast(unsigned, b); }
; template <bool NT_LD, bool NT_ST> DI void norm_row2(const float* xrow0, const float* xrow1, const float* g, const float* sc, const float* sh, bf16* obf0, bf16* obf1, float* of0, float* of1, int lane) {
;     ...
;     for (int j = 0; j < 8; ++j) {
;         const int c4 = lane + 64 * j;
;         const f32x4 gg = ((const f32x4*)g)[c4];
;         f32x4 y0 = v0[j] * r0 * gg, y1 = v1[j] * r1 * gg;
;         if (sc) { const f32x4 a = ((const f32x4*)sc)[c4] + 1.0f, bsh = ((const f32x4*)sh)[c4]; y0 = y0 * a + bsh; y1 = y1 * a + bsh; }
;         if (obf0) { u32x2 o0; o0.x = pk2(y0.x, y0.y); o0.y = pk2(y0.z, y0.w); ((u32x2*)obf0)[c4] = o0; u32x2 o1; o1.x = pk2(y1.x, y1.y); o1.y = pk2(y1.z, y1.w); ((u32x2*)obf1)[c4] = o1; }
;         else if (NT_ST) { __builtin_nontemporal_store(y0, (f32x4*)of0 + c4); __builtin_nontemporal_store(y1, (f32x4*)of1 + c4); }
;         else { ((f32x4*)of0)[c4] = y0; ((f32x4*)of1)[c4] = y1; }
;     }
	v_pk_fma_f32 v[4:5], v[4:5], v[14:15], v[56:57]
	v_pk_fma_f32 v[2:3], v[2:3], v[12:13], v[54:55]
	v_pk_fma_f32 v[8:9], v[8:9], v[14:15], v[56:57]
	v_pk_fma_f32 v[6:7], v[6:7], v[12:13], v[54:55]
	v_cvt_pk_bf16_f32 v2, v2, v3
	v_cvt_pk_bf16_f32 v3, v4, v5
	v_cvt_pk_bf16_f32 v4, v6, v7
	v_cvt_pk_bf16_f32 v5, v8, v9
	global_store_dwordx2 v[74:75], v[2:3], off offset:1536
	global_store_dwordx2 v[78:79], v[4:5], off offset:1536
	global_load_dwordx4 v[2:5], v[66:67], off
	s_nop 0
	global_load_dwordx4 v[6:9], v[80:81], off
	global_load_dwordx4 v[12:15], v[82:83], off
	v_pk_mul_f32 v[16:17], v[44:45], v[84:85] op_sel_hi:[1,0]
	v_pk_mul_f32 v[44:45], v[48:49], v[10:11] op_sel_hi:[1,0]
	s_waitcnt vmcnt(2)
	v_pk_mul_f32 v[42:43], v[42:43], v[2:3]
	v_pk_mul_f32 v[16:17], v[16:17], v[4:5]
	s_waitcnt vmcnt(1)
	v_pk_add_f32 v[8:9], v[8:9], 1.0 op_sel_hi:[1,0]
	v_pk_add_f32 v[6:7], v[6:7], 1.0 op_sel_hi:[1,0]
	v_pk_mul_f32 v[2:3], v[46:47], v[2:3]
	v_pk_mul_f32 v[4:5], v[44:45], v[4:5]
	s_waitcnt vmcnt(0)
	v_pk_fma_f32 v[16:17], v[16:17], v[8:9], v[14:15]
	v_pk_fma_f32 v[42:43], v[42:43], v[6:7], v[12:13]
	v_pk_fma_f32 v[4:5], v[4:5], v[8:9], v[14:15]
	v_pk_fma_f32 v[2:3], v[2:3], v[6:7], v[12:13]
	v_cvt_pk_bf16_f32 v6, v42, v43
	v_cvt_pk_bf16_f32 v7, v16, v17
	v_cvt_pk_bf16_f32 v2, v2, v3
	v_cvt_pk_bf16_f32 v3, v4, v5
	global_store_dwordx2 v[74:75], v[6:7], off offset:2048
	global_store_dwordx2 v[78:79], v[2:3], off offset:2048
	global_load_dwordx4 v[2:5], v[68:69], off
	s_nop 0
	global_load_dwordx4 v[6:9], v[80:81], off offset:1024
	global_load_dwordx4 v[12:15], v[82:83], off offset:1024
	v_pk_mul_f32 v[16:17], v[36:37], v[84:85] op_sel_hi:[1,0]
	v_pk_mul_f32 v[36:37], v[40:41], v[10:11] op_sel_hi:[1,0]
	s_waitcnt vmcnt(2)
	v_pk_mul_f32 v[34:35], v[34:35], v[2:3]
	v_pk_mul_f32 v[16:17], v[16:17], v[4:5]
	s_waitcnt vmcnt(1)
	v_pk_add_f32 v[8:9], v[8:9], 1.0 op_sel_hi:[1,0]
	v_pk_add_f32 v[6:7], v[6:7], 1.0 op_sel_hi:[1,0]
	v_pk_mul_f32 v[2:3], v[38:39], v[2:3]
	v_pk_mul_f32 v[4:5], v[36:37], v[4:5]
	s_waitcnt vmcnt(0)
	v_pk_fma_f32 v[16:17], v[16:17], v[8:9], v[14:15]
	v_pk_fma_f32 v[34:35], v[34:35], v[6:7], v[12:13]
	v_pk_fma_f32 v[4:5], v[4:5], v[8:9], v[14:15]
	v_pk_fma_f32 v[2:3], v[2:3], v[6:7], v[12:13]
	v_cvt_pk_bf16_f32 v6, v34, v35
	v_cvt_pk_bf16_f32 v7, v16, v17
	v_cvt_pk_bf16_f32 v2, v2, v3
	v_cvt_pk_bf16_f32 v3, v4, v5
	global_store_dwordx2 v[74:75], v[6:7], off offset:2560
	global_store_dwordx2 v[78:79], v[2:3], off offset:2560
	global_load_dwordx4 v[2:5], v[70:71], off
	s_nop 0
	global_load_dwordx4 v[6:9], v[80:81], off offset:2048
	global_load_dwordx4 v[12:15], v[82:83], off offset:2048
	v_pk_mul_f32 v[16:17], v[28:29], v[84:85] op_sel_hi:[1,0]
	v_pk_mul_f32 v[28:29], v[32:33], v[10:11] op_sel_hi:[1,0]
	s_waitcnt vmcnt(2)
	v_pk_mul_f32 v[26:27], v[26:27], v[2:3]
	v_pk_mul_f32 v[16:17], v[16:17], v[4:5]
	s_waitcnt vmcnt(1)
	v_pk_add_f32 v[8:9], v[8:9], 1.0 op_sel_hi:[1,0]
	v_pk_add_f32 v[6:7], v[6:7], 1.0 op_sel_hi:[1,0]
	v_pk_mul_f32 v[2:3], v[30:31], v[2:3]
	v_pk_mul_f32 v[4:5], v[28:29], v[4:5]
	s_waitcnt vmcnt(0)
	v_pk_fma_f32 v[16:17], v[16:17], v[8:9], v[14:15]
	v_pk_fma_f32 v[26:27], v[26:27], v[6:7], v[12:13]
	v_pk_fma_f32 v[4:5], v[4:5], v[8:9], v[14:15]
	v_pk_fma_f32 v[2:3], v[2:3], v[6:7], v[12:13]
	v_cvt_pk_bf16_f32 v6, v26, v27
	v_cvt_pk_bf16_f32 v7, v16, v17
	v_cvt_pk_bf16_f32 v2, v2, v3
	v_cvt_pk_bf16_f32 v3, v4, v5
	global_store_dwordx2 v[74:75], v[6:7], off offset:3072
	global_store_dwordx2 v[78:79], v[2:3], off offset:3072
	global_load_dwordx4 v[2:5], v[72:73], off
	s_nop 0
	global_load_dwordx4 v[6:9], v[80:81], off offset:3072
	global_load_dwordx4 v[12:15], v[82:83], off offset:3072
	v_pk_mul_f32 v[16:17], v[20:21], v[84:85] op_sel_hi:[1,0]
	v_pk_mul_f32 v[20:21], v[24:25], v[10:11] op_sel_hi:[1,0]
	v_pk_mul_f32 v[10:11], v[22:23], v[10:11] op_sel_hi:[1,0]
	s_waitcnt vmcnt(2)
	v_pk_mul_f32 v[18:19], v[18:19], v[2:3]
	v_pk_mul_f32 v[16:17], v[16:17], v[4:5]
	s_waitcnt vmcnt(1)
	v_pk_add_f32 v[8:9], v[8:9], 1.0 op_sel_hi:[1,0]
	v_pk_add_f32 v[6:7], v[6:7], 1.0 op_sel_hi:[1,0]
	v_pk_mul_f32 v[2:3], v[10:11], v[2:3]
	v_pk_mul_f32 v[4:5], v[20:21], v[4:5]
	s_waitcnt vmcnt(0)
	v_pk_fma_f32 v[10:11], v[16:17], v[8:9], v[14:15]
	v_pk_fma_f32 v[16:17], v[18:19], v[6:7], v[12:13]
	v_pk_fma_f32 v[4:5], v[4:5], v[8:9], v[14:15]
	v_pk_fma_f32 v[2:3], v[2:3], v[6:7], v[12:13]
	v_cvt_pk_bf16_f32 v6, v16, v17
	v_cvt_pk_bf16_f32 v7, v10, v11
	v_cvt_pk_bf16_f32 v2, v2, v3
	v_cvt_pk_bf16_f32 v3, v4, v5
	global_store_dwordx2 v[74:75], v[6:7], off offset:3584
	global_store_dwordx2 v[78:79], v[2:3], off offset:3584
	v_lshl_add_u64 v[74:75], v[74:75], 0, s[18:19]
	s_cbranch_scc1 .LBB0_1019

;     __device__ __forceinline__ void operator()(const f32x4 (&acc)[2][2][4][2], const Unit& u, int wr, int wc, int fr, int fq) const {
;     ...
;             for (int m = 0; m < 4; ++m) { const size_t off = (size_t)(u.pm * BM + ai * HALF + wr * 64 + m * 16 + fr) * 2048 + col0;
; #pragma unroll
;                 for (int bj = 0; bj < 2; ++bj)
; #pragma unroll
;                     for (int n = 0; n < 2; ++n) { const f32x4 bs = *(const f32x4*)(base + off + bj * HALF + n * 16);
;                         *(f32x4*)(out + off + bj * HALF + n * 16) = bs + gv[bj][n] * acc[ai][bj][m][n]; }
;                 if (m & 1) asm volatile("" ::: "memory"); }
.LBB0_1198:
	s_ashr_i32 s22, s45, 5
	v_lshl_or_b32 v130, s46, 8, v164
	v_lshl_add_u32 v160, s45, 8, v162
	s_mul_hi_i32 s23, s22, 0xc000
	s_mul_i32 s22, s22, 0xc000
	v_ashrrev_i32_e32 v131, 31, v130
	v_ashrrev_i32_e32 v161, 31, v160
	s_add_u32 s22, s35, s22
	v_lshlrev_b64 v[158:159], 2, v[130:131]
	v_lshlrev_b64 v[130:131], 13, v[160:161]
	v_or_b32_e32 v188, 16, v160
	s_addc_u32 s23, s36, s23
	v_lshl_add_u64 v[130:131], s[12:13], 0, v[130:131]
	v_ashrrev_i32_e32 v189, 31, v188
	v_lshl_add_u64 v[138:139], s[22:23], 0, v[158:159]
	v_lshl_add_u64 v[184:185], v[130:131], 0, v[158:159]
	v_lshlrev_b64 v[188:189], 13, v[188:189]
	global_load_dwordx4 v[168:171], v[184:185], off nt
	global_load_dwordx4 v[134:137], v[138:139], off
	global_load_dwordx4 v[130:133], v[138:139], off offset:64
	global_load_dwordx4 v[172:175], v[184:185], off offset:64 nt
	global_load_dwordx4 v[176:179], v[184:185], off offset:512 nt
	global_load_dwordx4 v[142:145], v[138:139], off offset:512
	s_nop 0
	global_load_dwordx4 v[138:141], v[138:139], off offset:576
	s_nop 0
	global_load_dwordx4 v[180:183], v[184:185], off offset:576 nt
	v_lshl_add_u64 v[188:189], s[12:13], 0, v[188:189]
	v_lshl_add_u64 v[204:205], v[188:189], 0, v[158:159]
	global_load_dwordx4 v[188:191], v[204:205], off nt
	global_load_dwordx4 v[192:195], v[204:205], off offset:64 nt
	global_load_dwordx4 v[196:199], v[204:205], off offset:512 nt
	global_load_dwordx4 v[200:203], v[204:205], off offset:576 nt
	v_or_b32_e32 v206, 32, v160
	v_or_b32_e32 v208, 48, v160
	v_ashrrev_i32_e32 v207, 31, v206
	v_lshlrev_b64 v[206:207], 13, v[206:207]
	v_ashrrev_i32_e32 v209, 31, v208
	v_lshl_add_u64 v[206:207], s[12:13], 0, v[206:207]
	v_lshl_add_u64 v[206:207], v[206:207], 0, v[158:159]
	s_and_b64 vcc, exec, s[0:1]
	s_mov_b64 s[0:1], -1
	s_waitcnt vmcnt(0)
	v_pk_fma_f32 v[128:129], v[128:129], v[136:137], v[170:171]
	v_pk_fma_f32 v[126:127], v[126:127], v[134:135], v[168:169]
	v_pk_fma_f32 v[124:125], v[124:125], v[132:133], v[174:175]
	v_pk_fma_f32 v[122:123], v[122:123], v[130:131], v[172:173]
	v_pk_fma_f32 v[110:111], v[110:111], v[142:143], v[176:177]
	v_pk_fma_f32 v[112:113], v[112:113], v[144:145], v[178:179]
	v_pk_fma_f32 v[108:109], v[108:109], v[140:141], v[182:183]
	v_pk_fma_f32 v[106:107], v[106:107], v[138:139], v[180:181]
	global_store_dwordx4 v[184:185], v[126:129], off nt
	global_store_dwordx4 v[184:185], v[122:125], off offset:64 nt
	global_store_dwordx4 v[184:185], v[110:113], off offset:512 nt
	global_store_dwordx4 v[184:185], v[106:109], off offset:576 nt
	v_pk_fma_f32 v[104:105], v[104:105], v[144:145], v[198:199]
	v_pk_fma_f32 v[110:111], v[114:115], v[130:131], v[192:193]
	v_pk_fma_f32 v[108:109], v[120:121], v[136:137], v[190:191]
	v_pk_fma_f32 v[106:107], v[118:119], v[134:135], v[188:189]
	v_pk_fma_f32 v[112:113], v[116:117], v[132:133], v[194:195]
	v_pk_fma_f32 v[102:103], v[102:103], v[142:143], v[196:197]
	v_pk_fma_f32 v[100:101], v[100:101], v[140:141], v[202:203]
	v_pk_fma_f32 v[98:99], v[98:99], v[138:139], v[200:201]
	global_store_dwordx4 v[204:205], v[106:109], off nt
	global_store_dwordx4 v[204:205], v[110:113], off offset:64 nt
	global_store_dwordx4 v[204:205], v[102:105], off offset:512 nt
	global_store_dwordx4 v[204:205], v[98:101], off offset:576 nt
	v_lshlrev_b64 v[110:111], 13, v[208:209]
	v_lshl_add_u64 v[114:115], s[12:13], 0, v[110:111]
	global_load_dwordx4 v[98:101], v[206:207], off nt
	global_load_dwordx4 v[102:105], v[206:207], off offset:64 nt
	global_load_dwordx4 v[106:109], v[206:207], off offset:512 nt
	global_load_dwordx4 v[110:113], v[206:207], off offset:576 nt
	v_lshl_add_u64 v[168:169], v[114:115], 0, v[158:159]
	global_load_dwordx4 v[114:117], v[168:169], off nt
	global_load_dwordx4 v[118:121], v[168:169], off offset:64 nt
	global_load_dwordx4 v[122:125], v[168:169], off offset:512 nt
	global_load_dwordx4 v[126:129], v[168:169], off offset:576 nt
	v_add_u32_e32 v170, 0x80, v160
	v_add_u32_e32 v172, 0x90, v160
	v_ashrrev_i32_e32 v171, 31, v170
	v_lshlrev_b64 v[170:171], 13, v[170:171]
	v_ashrrev_i32_e32 v173, 31, v172
	v_lshl_add_u64 v[170:171], s[12:13], 0, v[170:171]
	v_lshl_add_u64 v[170:171], v[170:171], 0, v[158:159]
	s_waitcnt vmcnt(7)
	v_pk_fma_f32 v[96:97], v[96:97], v[136:137], v[100:101]
	v_pk_fma_f32 v[94:95], v[94:95], v[134:135], v[98:99]
	s_waitcnt vmcnt(5)
	v_pk_fma_f32 v[78:79], v[78:79], v[142:143], v[106:107]
	v_pk_fma_f32 v[92:93], v[92:93], v[132:133], v[104:105]
	v_pk_fma_f32 v[90:91], v[90:91], v[130:131], v[102:103]
	v_pk_fma_f32 v[80:81], v[80:81], v[144:145], v[108:109]
	s_waitcnt vmcnt(4)
	v_pk_fma_f32 v[76:77], v[76:77], v[140:141], v[112:113]
	v_pk_fma_f32 v[74:75], v[74:75], v[138:139], v[110:111]
	s_waitcnt vmcnt(3)
	v_pk_fma_f32 v[88:89], v[88:89], v[136:137], v[116:117]
	v_pk_fma_f32 v[86:87], v[86:87], v[134:135], v[114:115]
	s_waitcnt vmcnt(2)
	v_pk_fma_f32 v[84:85], v[84:85], v[132:133], v[120:121]
	v_pk_fma_f32 v[82:83], v[82:83], v[130:131], v[118:119]
	s_waitcnt vmcnt(1)
	v_pk_fma_f32 v[72:73], v[72:73], v[144:145], v[124:125]
	v_pk_fma_f32 v[70:71], v[70:71], v[142:143], v[122:123]
	s_waitcnt vmcnt(0)
;     __device__ __forceinline__ void operator()(const f32x4 (&acc)[2][2][4][2], const Unit& u, int wr, int wc, int fr, int fq) const {
;     ...
;             for (int m = 0; m < 4; ++m) { const size_t off = (size_t)(u.pm * BM + ai * HALF + wr * 64 + m * 16 + fr) * 2048 + col0;
; #pragma unroll
;                 for (int bj = 0; bj < 2; ++bj)
; #pragma unroll
;                     for (int n = 0; n < 2; ++n) { const f32x4 bs = *(const f32x4*)(base + off + bj * HALF + n * 16);
;                         *(f32x4*)(out + off + bj * HALF + n * 16) = bs + gv[bj][n] * acc[ai][bj][m][n]; }
;                 if (m & 1) asm volatile("" ::: "memory"); }
	v_pk_fma_f32 v[68:69], v[68:69], v[140:141], v[128:129]
	v_pk_fma_f32 v[66:67], v[66:67], v[138:139], v[126:127]
	global_store_dwordx4 v[206:207], v[94:97], off nt
	global_store_dwordx4 v[206:207], v[90:93], off offset:64 nt
	global_store_dwordx4 v[206:207], v[78:81], off offset:512 nt
	global_store_dwordx4 v[206:207], v[74:77], off offset:576 nt
	global_store_dwordx4 v[168:169], v[86:89], off nt
	global_store_dwordx4 v[168:169], v[82:85], off offset:64 nt
	global_store_dwordx4 v[168:169], v[70:73], off offset:512 nt
	global_store_dwordx4 v[168:169], v[66:69], off offset:576 nt
	v_lshlrev_b64 v[78:79], 13, v[172:173]
	v_lshl_add_u64 v[82:83], s[12:13], 0, v[78:79]
	global_load_dwordx4 v[66:69], v[170:171], off nt
	global_load_dwordx4 v[70:73], v[170:171], off offset:64 nt
	global_load_dwordx4 v[74:77], v[170:171], off offset:512 nt
	global_load_dwordx4 v[78:81], v[170:171], off offset:576 nt
	v_lshl_add_u64 v[98:99], v[82:83], 0, v[158:159]
	global_load_dwordx4 v[82:85], v[98:99], off nt
	global_load_dwordx4 v[86:89], v[98:99], off offset:64 nt
	global_load_dwordx4 v[90:93], v[98:99], off offset:512 nt
	global_load_dwordx4 v[94:97], v[98:99], off offset:576 nt
	v_add_u32_e32 v100, 0xa0, v160
	v_add_u32_e32 v102, 0xb0, v160
	v_ashrrev_i32_e32 v101, 31, v100
	v_lshlrev_b64 v[100:101], 13, v[100:101]
	v_ashrrev_i32_e32 v103, 31, v102
	v_lshl_add_u64 v[100:101], s[12:13], 0, v[100:101]
	v_lshl_add_u64 v[100:101], v[100:101], 0, v[158:159]
	s_waitcnt vmcnt(7)
	v_pk_fma_f32 v[64:65], v[64:65], v[136:137], v[68:69]
	v_pk_fma_f32 v[62:63], v[62:63], v[134:135], v[66:67]
	s_waitcnt vmcnt(5)
	v_pk_fma_f32 v[46:47], v[46:47], v[142:143], v[74:75]
	v_pk_fma_f32 v[60:61], v[60:61], v[132:133], v[72:73]
	v_pk_fma_f32 v[58:59], v[58:59], v[130:131], v[70:71]
	v_pk_fma_f32 v[48:49], v[48:49], v[144:145], v[76:77]
	s_waitcnt vmcnt(4)
	v_pk_fma_f32 v[44:45], v[44:45], v[140:141], v[80:81]
	v_pk_fma_f32 v[42:43], v[42:43], v[138:139], v[78:79]
	s_waitcnt vmcnt(3)
	v_pk_fma_f32 v[56:57], v[56:57], v[136:137], v[84:85]
	v_pk_fma_f32 v[54:55], v[54:55], v[134:135], v[82:83]
	s_waitcnt vmcnt(2)
	v_pk_fma_f32 v[52:53], v[52:53], v[132:133], v[88:89]
	v_pk_fma_f32 v[50:51], v[50:51], v[130:131], v[86:87]
	s_waitcnt vmcnt(1)
	v_pk_fma_f32 v[40:41], v[40:41], v[144:145], v[92:93]
	v_pk_fma_f32 v[38:39], v[38:39], v[142:143], v[90:91]
	s_waitcnt vmcnt(0)
	v_pk_fma_f32 v[36:37], v[36:37], v[140:141], v[96:97]
	v_pk_fma_f32 v[34:35], v[34:35], v[138:139], v[94:95]
	global_store_dwordx4 v[170:171], v[62:65], off nt
	global_store_dwordx4 v[170:171], v[58:61], off offset:64 nt
	global_store_dwordx4 v[170:171], v[46:49], off offset:512 nt
	global_store_dwordx4 v[170:171], v[42:45], off offset:576 nt
	global_store_dwordx4 v[98:99], v[54:57], off nt
	global_store_dwordx4 v[98:99], v[50:53], off offset:64 nt
	global_store_dwordx4 v[98:99], v[38:41], off offset:512 nt
	global_store_dwordx4 v[98:99], v[34:37], off offset:576 nt
	v_lshlrev_b64 v[46:47], 13, v[102:103]
	v_lshl_add_u64 v[50:51], s[12:13], 0, v[46:47]
	global_load_dwordx4 v[34:37], v[100:101], off nt
	global_load_dwordx4 v[38:41], v[100:101], off offset:64 nt
	v_lshl_add_u64 v[66:67], v[50:51], 0, v[158:159]
	global_load_dwordx4 v[42:45], v[100:101], off offset:512 nt
	global_load_dwordx4 v[46:49], v[100:101], off offset:576 nt
	global_load_dwordx4 v[50:53], v[66:67], off nt
	global_load_dwordx4 v[54:57], v[66:67], off offset:64 nt
	global_load_dwordx4 v[58:61], v[66:67], off offset:512 nt
	global_load_dwordx4 v[62:65], v[66:67], off offset:576 nt
	s_waitcnt vmcnt(7)
	v_pk_fma_f32 v[32:33], v[32:33], v[136:137], v[36:37]
	v_pk_fma_f32 v[30:31], v[30:31], v[134:135], v[34:35]
	s_waitcnt vmcnt(6)
	v_pk_fma_f32 v[28:29], v[28:29], v[132:133], v[40:41]
	v_pk_fma_f32 v[26:27], v[26:27], v[130:131], v[38:39]
	s_waitcnt vmcnt(5)
	v_pk_fma_f32 v[16:17], v[16:17], v[144:145], v[44:45]
	v_pk_fma_f32 v[14:15], v[14:15], v[142:143], v[42:43]
	s_waitcnt vmcnt(4)
	v_pk_fma_f32 v[12:13], v[12:13], v[140:141], v[48:49]
	v_pk_fma_f32 v[10:11], v[10:11], v[138:139], v[46:47]
	s_waitcnt vmcnt(3)
	v_pk_fma_f32 v[24:25], v[24:25], v[136:137], v[52:53]
	v_pk_fma_f32 v[22:23], v[22:23], v[134:135], v[50:51]
	s_waitcnt vmcnt(2)
	v_pk_fma_f32 v[20:21], v[20:21], v[132:133], v[56:57]
	v_pk_fma_f32 v[18:19], v[18:19], v[130:131], v[54:55]
	s_waitcnt vmcnt(1)
	v_pk_fma_f32 v[8:9], v[8:9], v[144:145], v[60:61]
	v_pk_fma_f32 v[6:7], v[6:7], v[142:143], v[58:59]
	s_waitcnt vmcnt(0)
	v_pk_fma_f32 v[4:5], v[4:5], v[140:141], v[64:65]
	v_pk_fma_f32 v[2:3], v[2:3], v[138:139], v[62:63]
	global_store_dwordx4 v[100:101], v[30:33], off nt
	global_store_dwordx4 v[100:101], v[26:29], off offset:64 nt
	global_store_dwordx4 v[100:101], v[14:17], off offset:512 nt
	global_store_dwordx4 v[100:101], v[10:13], off offset:576 nt
	global_store_dwordx4 v[66:67], v[22:25], off nt
	global_store_dwordx4 v[66:67], v[18:21], off offset:64 nt
	global_store_dwordx4 v[66:67], v[6:9], off offset:512 nt
	global_store_dwordx4 v[66:67], v[2:5], off offset:576 nt
	s_cbranch_vccnz .LBB0_1183
	s_andn2_b64 vcc, exec, s[8:9]
	s_cbranch_vccnz .LBB0_1182
	s_barrier
	s_branch .LBB0_1182
